# gMLP mixer epilogue: issue the U-row loads up front (counted waits) instead of a load+store round trip per row group
# speedup vs baseline: 1.0044x; 1.0044x over previous
.LBB0_213:
	s_lshl_b32 s24, s24, 7
	s_ashr_i32 s25, s24, 31
	s_mul_i32 s34, s6, 0x600
	s_mul_hi_i32 s8, s6, 0x600
	s_add_u32 s34, s36, s34
	s_addc_u32 s8, s37, s8
	s_lshl_b64 s[6:7], s[6:7], 11
	s_add_u32 s35, s79, s6
	s_addc_u32 s39, s80, s7
	s_lshl_b64 s[6:7], s[24:25], 2
	s_add_u32 s42, s2, s6
	s_addc_u32 s43, s3, s7
	s_add_u32 s6, s40, s47
	s_addc_u32 s7, s41, 0
	s_lshl_b64 s[2:3], s[16:17], 2
	s_add_u32 s24, s6, s2
	s_addc_u32 s25, s7, s3
	s_lshl_b64 s[6:7], s[16:17], 1
	s_add_u32 s2, s34, s6
	s_addc_u32 s3, s8, s7
	s_add_u32 s6, s35, s6
	s_addc_u32 s7, s39, s7
	s_lshl_b32 s8, s38, 2
	s_add_u32 s16, s42, s8
	s_waitcnt vmcnt(6)
	v_lshlrev_b32_e32 v64, 2, v193
	s_addc_u32 s17, s43, 0
	v_ashrrev_i32_e32 v65, 31, v64
	v_lshl_add_u64 v[64:65], v[64:65], 2, s[16:17]
	s_waitcnt vmcnt(3)
	v_lshlrev_b32_e32 v81, 2, v192
	global_load_dwordx4 v[76:79], v[64:65], off
	global_load_dwordx4 v[72:75], v[64:65], off offset:32
	global_load_dwordx4 v[68:71], v[64:65], off offset:64
	s_nop 0
	global_load_dwordx4 v[64:67], v[64:65], off offset:96
	v_lshlrev_b32_e32 v80, 11, v193
	global_load_dword v82, v81, s[24:25]
	v_add3_u32 v80, s33, v80, v81
	v_add_u32_e32 v144, s38, v147
	s_waitcnt vmcnt(0)
	v_fma_f32 v48, v48, v82, v76
	v_fma_f32 v49, v49, v82, v77
	v_fma_f32 v50, v50, v82, v78
	v_fma_f32 v51, v51, v82, v79
	v_fma_f32 v52, v52, v82, v72
	v_fma_f32 v53, v53, v82, v73
	v_fma_f32 v54, v54, v82, v74
	v_fma_f32 v55, v55, v82, v75
	v_fma_f32 v56, v56, v82, v68
	v_fma_f32 v57, v57, v82, v69
	v_fma_f32 v58, v58, v82, v70
	v_fma_f32 v59, v59, v82, v71
	v_fma_f32 v60, v60, v82, v64
	v_fma_f32 v61, v61, v82, v65
	v_fma_f32 v62, v62, v82, v66
	v_fma_f32 v63, v63, v82, v67
	global_load_dword v82, v81, s[24:25] offset:128
	s_waitcnt vmcnt(0)
	v_fma_f32 v32, v32, v82, v76
	ds_write2_b32 v80, v48, v32 offset1:32
	v_fma_f32 v32, v33, v82, v77
	ds_write2_b32 v80, v49, v32 offset0:128 offset1:160
	v_fma_f32 v32, v34, v82, v78
	v_add_u32_e32 v33, 0x400, v80
	ds_write2_b32 v33, v50, v32 offset1:32
	v_fma_f32 v32, v35, v82, v79
	ds_write2_b32 v33, v51, v32 offset0:128 offset1:160
	v_fma_f32 v32, v36, v82, v72
	v_add_u32_e32 v34, 0x1000, v80
	ds_write2_b32 v34, v52, v32 offset1:32
	v_fma_f32 v32, v37, v82, v73
	ds_write2_b32 v34, v53, v32 offset0:128 offset1:160
	v_fma_f32 v32, v38, v82, v74
	v_add_u32_e32 v35, 0x1400, v80
	ds_write2_b32 v35, v54, v32 offset1:32
	v_fma_f32 v32, v39, v82, v75
	ds_write2_b32 v35, v55, v32 offset0:128 offset1:160
	v_fma_f32 v32, v40, v82, v68
	v_add_u32_e32 v36, 0x2000, v80
	ds_write2_b32 v36, v56, v32 offset1:32
	v_fma_f32 v32, v41, v82, v69
	ds_write2_b32 v36, v57, v32 offset0:128 offset1:160
	v_fma_f32 v32, v42, v82, v70
	v_add_u32_e32 v37, 0x2400, v80
	ds_write2_b32 v37, v58, v32 offset1:32
	v_fma_f32 v32, v43, v82, v71
	ds_write2_b32 v37, v59, v32 offset0:128 offset1:160
	v_fma_f32 v32, v44, v82, v64
	v_add_u32_e32 v38, 0x3000, v80
	ds_write2_b32 v38, v60, v32 offset1:32
	v_fma_f32 v32, v45, v82, v65
	ds_write2_b32 v38, v61, v32 offset0:128 offset1:160
	v_fma_f32 v32, v46, v82, v66
	v_add_u32_e32 v39, 0x3400, v80
	ds_write2_b32 v39, v62, v32 offset1:32
	v_fma_f32 v32, v47, v82, v67
	ds_write2_b32 v39, v63, v32 offset0:128 offset1:160
	global_load_dword v32, v81, s[24:25] offset:256
	s_waitcnt vmcnt(0)
	v_fma_f32 v16, v16, v32, v76
	v_fma_f32 v17, v17, v32, v77
	v_fma_f32 v18, v18, v32, v78
	v_fma_f32 v19, v19, v32, v79
	v_fma_f32 v20, v20, v32, v72
	v_fma_f32 v21, v21, v32, v73
	v_fma_f32 v22, v22, v32, v74
	v_fma_f32 v23, v23, v32, v75
	v_fma_f32 v24, v24, v32, v68
	v_fma_f32 v25, v25, v32, v69
	v_fma_f32 v26, v26, v32, v70
	v_fma_f32 v27, v27, v32, v71
	v_fma_f32 v28, v28, v32, v64
	v_fma_f32 v29, v29, v32, v65
	v_fma_f32 v30, v30, v32, v66
	v_fma_f32 v31, v31, v32, v67
	global_load_dword v32, v81, s[24:25] offset:384
	s_waitcnt vmcnt(0)
	v_fma_f32 v0, v0, v32, v76
	ds_write2_b32 v80, v16, v0 offset0:64 offset1:96
	v_fma_f32 v0, v1, v32, v77
	ds_write2_b32 v80, v17, v0 offset0:192 offset1:224
	v_fma_f32 v0, v2, v32, v78
	ds_write2_b32 v33, v18, v0 offset0:64 offset1:96
	v_fma_f32 v0, v4, v32, v72
	ds_write2_b32 v34, v20, v0 offset0:64 offset1:96
	v_fma_f32 v0, v5, v32, v73
	ds_write2_b32 v34, v21, v0 offset0:192 offset1:224
	v_fma_f32 v0, v6, v32, v74
	ds_write2_b32 v35, v22, v0 offset0:64 offset1:96
	v_fma_f32 v0, v8, v32, v68
	ds_write2_b32 v36, v24, v0 offset0:64 offset1:96
	v_fma_f32 v0, v9, v32, v69
	ds_write2_b32 v36, v25, v0 offset0:192 offset1:224
	v_fma_f32 v0, v10, v32, v70
	ds_write2_b32 v37, v26, v0 offset0:64 offset1:96
	v_fma_f32 v0, v12, v32, v64
	ds_write2_b32 v38, v28, v0 offset0:64 offset1:96
	v_fma_f32 v0, v13, v32, v65
	ds_write2_b32 v38, v29, v0 offset0:192 offset1:224
	v_fma_f32 v0, v14, v32, v66
	ds_write2_b32 v39, v30, v0 offset0:64 offset1:96
	v_lshl_add_u64 v[0:1], s[2:3], 0, v[158:159]
	v_fmac_f32_e32 v79, v3, v32
	v_mad_i64_i32 v[2:3], s[2:3], v148, s69, v[0:1]
	v_fmac_f32_e32 v71, v11, v32
	global_load_dwordx4 v[8:11], v[2:3], off
	v_add_u32_e32 v96, s38, v205
	v_mad_i64_i32 v[98:99], s[2:3], v96, s69, v[0:1]
	global_load_dwordx4 v[100:103], v[98:99], off
	v_add_u32_e32 v96, s38, v202
	v_mad_i64_i32 v[98:99], s[2:3], v96, s69, v[0:1]
	global_load_dwordx4 v[104:107], v[98:99], off
	v_add_u32_e32 v96, s38, v201
	v_mad_i64_i32 v[98:99], s[2:3], v96, s69, v[0:1]
	global_load_dwordx4 v[108:111], v[98:99], off
	v_add_u32_e32 v96, s38, v200
	v_mad_i64_i32 v[98:99], s[2:3], v96, s69, v[0:1]
	global_load_dwordx4 v[112:115], v[98:99], off
	v_add_u32_e32 v96, s38, v199
	v_mad_i64_i32 v[98:99], s[2:3], v96, s69, v[0:1]
	global_load_dwordx4 v[116:119], v[98:99], off
	v_add_u32_e32 v96, s38, v145
	v_mad_i64_i32 v[98:99], s[2:3], v96, s69, v[0:1]
	global_load_dwordx4 v[120:123], v[98:99], off
	v_fmac_f32_e32 v75, v7, v32
	v_fmac_f32_e32 v67, v15, v32
	v_lshl_add_u32 v6, v149, 5, s33
	ds_write2_b32 v33, v19, v79 offset0:192 offset1:224
	ds_write2_b32 v35, v23, v75 offset0:192 offset1:224
	ds_write2_b32 v37, v27, v71 offset0:192 offset1:224
	ds_write2_b32 v39, v31, v67 offset0:192 offset1:224
	v_lshl_add_u32 v2, v213, 9, v6
	ds_read_b128 v[12:15], v2
	ds_read_b128 v[16:19], v2 offset:16
	v_ashrrev_i32_e32 v149, 31, v148
	v_lshl_add_u64 v[4:5], s[6:7], 0, v[158:159]
	v_lshl_add_u32 v7, v205, 9, v6
	s_waitcnt vmcnt(6)
	v_lshlrev_b32_e32 v2, 16, v8
	v_and_b32_e32 v3, 0xffff0000, v8
	s_waitcnt lgkmcnt(1)
	v_pk_mul_f32 v[2:3], v[12:13], v[2:3]
	s_nop 0
	v_cvt_pk_bf16_f32 v8, v2, v3
	v_lshlrev_b32_e32 v2, 16, v9
	v_and_b32_e32 v3, 0xffff0000, v9
	v_pk_mul_f32 v[2:3], v[14:15], v[2:3]
	s_nop 0
	v_cvt_pk_bf16_f32 v9, v2, v3
	v_lshlrev_b32_e32 v2, 16, v10
	v_and_b32_e32 v3, 0xffff0000, v10
	s_waitcnt lgkmcnt(0)
	v_pk_mul_f32 v[2:3], v[16:17], v[2:3]
	s_nop 0
	v_cvt_pk_bf16_f32 v10, v2, v3
	v_lshlrev_b32_e32 v2, 16, v11
	v_and_b32_e32 v3, 0xffff0000, v11
	v_pk_mul_f32 v[2:3], v[18:19], v[2:3]
	s_nop 0
	v_cvt_pk_bf16_f32 v11, v2, v3
	v_lshlrev_b64 v[2:3], 11, v[148:149]
	v_lshl_add_u64 v[2:3], v[4:5], 0, v[2:3]
	global_store_dwordx4 v[2:3], v[8:11], off sc1
	v_add_u32_e32 v2, s38, v205
	v_ashrrev_i32_e32 v3, 31, v2
	ds_read_b128 v[12:15], v7
	ds_read_b128 v[16:19], v7 offset:16
	v_lshlrev_b64 v[2:3], 11, v[2:3]
	v_lshl_add_u64 v[2:3], v[4:5], 0, v[2:3]
	v_lshl_add_u32 v7, v202, 9, v6
	s_waitcnt vmcnt(6)
	v_mov_b32_e32 v8, v100
	v_mov_b32_e32 v9, v101
	v_mov_b32_e32 v10, v102
	v_mov_b32_e32 v11, v103
	v_lshlrev_b32_e32 v20, 16, v8
	v_and_b32_e32 v21, 0xffff0000, v8
	s_waitcnt lgkmcnt(1)
	v_pk_mul_f32 v[12:13], v[12:13], v[20:21]
	s_nop 0
	v_cvt_pk_bf16_f32 v8, v12, v13
	v_lshlrev_b32_e32 v12, 16, v9
	v_and_b32_e32 v13, 0xffff0000, v9
	v_pk_mul_f32 v[12:13], v[14:15], v[12:13]
	s_nop 0
	v_cvt_pk_bf16_f32 v9, v12, v13
	v_lshlrev_b32_e32 v12, 16, v10
	v_and_b32_e32 v13, 0xffff0000, v10
	s_waitcnt lgkmcnt(0)
	v_pk_mul_f32 v[12:13], v[16:17], v[12:13]
	s_nop 0
	v_cvt_pk_bf16_f32 v10, v12, v13
	v_lshlrev_b32_e32 v12, 16, v11
	v_and_b32_e32 v13, 0xffff0000, v11
	v_pk_mul_f32 v[12:13], v[18:19], v[12:13]
	s_nop 0
	v_cvt_pk_bf16_f32 v11, v12, v13
	global_store_dwordx4 v[2:3], v[8:11], off sc1
	v_add_u32_e32 v2, s38, v202
	v_ashrrev_i32_e32 v3, 31, v2
	ds_read_b128 v[12:15], v7
	ds_read_b128 v[16:19], v7 offset:16
	v_lshlrev_b64 v[2:3], 11, v[2:3]
	v_lshl_add_u64 v[2:3], v[4:5], 0, v[2:3]
	v_lshl_add_u32 v7, v201, 9, v6
	s_waitcnt vmcnt(6)
	v_mov_b32_e32 v8, v104
	v_mov_b32_e32 v9, v105
	v_mov_b32_e32 v10, v106
	v_mov_b32_e32 v11, v107
	v_lshlrev_b32_e32 v20, 16, v8
	v_and_b32_e32 v21, 0xffff0000, v8
	s_waitcnt lgkmcnt(1)
	v_pk_mul_f32 v[12:13], v[12:13], v[20:21]
	s_nop 0
	v_cvt_pk_bf16_f32 v8, v12, v13
	v_lshlrev_b32_e32 v12, 16, v9
	v_and_b32_e32 v13, 0xffff0000, v9
	v_pk_mul_f32 v[12:13], v[14:15], v[12:13]
	s_nop 0
	v_cvt_pk_bf16_f32 v9, v12, v13
	v_lshlrev_b32_e32 v12, 16, v10
	v_and_b32_e32 v13, 0xffff0000, v10
	s_waitcnt lgkmcnt(0)
	v_pk_mul_f32 v[12:13], v[16:17], v[12:13]
	s_nop 0
	v_cvt_pk_bf16_f32 v10, v12, v13
	v_lshlrev_b32_e32 v12, 16, v11
	v_and_b32_e32 v13, 0xffff0000, v11
	v_pk_mul_f32 v[12:13], v[18:19], v[12:13]
	s_nop 0
	v_cvt_pk_bf16_f32 v11, v12, v13
	global_store_dwordx4 v[2:3], v[8:11], off sc1
	v_add_u32_e32 v2, s38, v201
	v_ashrrev_i32_e32 v3, 31, v2
	ds_read_b128 v[12:15], v7
	ds_read_b128 v[16:19], v7 offset:16
	v_lshlrev_b64 v[2:3], 11, v[2:3]
	v_lshl_add_u64 v[2:3], v[4:5], 0, v[2:3]
	v_lshl_add_u32 v7, v200, 9, v6
	s_waitcnt vmcnt(6)
	v_mov_b32_e32 v8, v108
	v_mov_b32_e32 v9, v109
	v_mov_b32_e32 v10, v110
	v_mov_b32_e32 v11, v111
	v_lshlrev_b32_e32 v20, 16, v8
	v_and_b32_e32 v21, 0xffff0000, v8
	s_waitcnt lgkmcnt(1)
	v_pk_mul_f32 v[12:13], v[12:13], v[20:21]
	s_nop 0
	v_cvt_pk_bf16_f32 v8, v12, v13
	v_lshlrev_b32_e32 v12, 16, v9
	v_and_b32_e32 v13, 0xffff0000, v9
	v_pk_mul_f32 v[12:13], v[14:15], v[12:13]
	s_nop 0
	v_cvt_pk_bf16_f32 v9, v12, v13
	v_lshlrev_b32_e32 v12, 16, v10
	v_and_b32_e32 v13, 0xffff0000, v10
	s_waitcnt lgkmcnt(0)
	v_pk_mul_f32 v[12:13], v[16:17], v[12:13]
	s_nop 0
	v_cvt_pk_bf16_f32 v10, v12, v13
	v_lshlrev_b32_e32 v12, 16, v11
	v_and_b32_e32 v13, 0xffff0000, v11
	v_pk_mul_f32 v[12:13], v[18:19], v[12:13]
	s_nop 0
	v_cvt_pk_bf16_f32 v11, v12, v13
	global_store_dwordx4 v[2:3], v[8:11], off sc1
	v_add_u32_e32 v2, s38, v200
	v_ashrrev_i32_e32 v3, 31, v2
	ds_read_b128 v[12:15], v7
	ds_read_b128 v[16:19], v7 offset:16
	v_lshlrev_b64 v[2:3], 11, v[2:3]
	v_lshl_add_u64 v[2:3], v[4:5], 0, v[2:3]
	v_lshl_add_u32 v7, v199, 9, v6
	s_waitcnt vmcnt(6)
	v_mov_b32_e32 v8, v112
	v_mov_b32_e32 v9, v113
	v_mov_b32_e32 v10, v114
	v_mov_b32_e32 v11, v115
	v_lshlrev_b32_e32 v20, 16, v8
	v_and_b32_e32 v21, 0xffff0000, v8
	s_waitcnt lgkmcnt(1)
	v_pk_mul_f32 v[12:13], v[12:13], v[20:21]
	s_nop 0
	v_cvt_pk_bf16_f32 v8, v12, v13
	v_lshlrev_b32_e32 v12, 16, v9
	v_and_b32_e32 v13, 0xffff0000, v9
	v_pk_mul_f32 v[12:13], v[14:15], v[12:13]
	s_nop 0
	v_cvt_pk_bf16_f32 v9, v12, v13
	v_lshlrev_b32_e32 v12, 16, v10
	v_and_b32_e32 v13, 0xffff0000, v10
	s_waitcnt lgkmcnt(0)
	v_pk_mul_f32 v[12:13], v[16:17], v[12:13]
	s_nop 0
	v_cvt_pk_bf16_f32 v10, v12, v13
	v_lshlrev_b32_e32 v12, 16, v11
	v_and_b32_e32 v13, 0xffff0000, v11
	v_pk_mul_f32 v[12:13], v[18:19], v[12:13]
	s_nop 0
	v_cvt_pk_bf16_f32 v11, v12, v13
	global_store_dwordx4 v[2:3], v[8:11], off sc1
	v_add_u32_e32 v2, s38, v199
	v_ashrrev_i32_e32 v3, 31, v2
	ds_read_b128 v[12:15], v7
	ds_read_b128 v[16:19], v7 offset:16
	v_lshlrev_b64 v[2:3], 11, v[2:3]
	v_lshl_add_u64 v[2:3], v[4:5], 0, v[2:3]
	v_lshl_add_u32 v7, v145, 9, v6
	s_waitcnt vmcnt(6)
	v_mov_b32_e32 v8, v116
	v_mov_b32_e32 v9, v117
	v_mov_b32_e32 v10, v118
	v_mov_b32_e32 v11, v119
	v_lshlrev_b32_e32 v20, 16, v8
	v_and_b32_e32 v21, 0xffff0000, v8
	s_waitcnt lgkmcnt(1)
	v_pk_mul_f32 v[12:13], v[12:13], v[20:21]
	s_nop 0
	v_cvt_pk_bf16_f32 v8, v12, v13
	v_lshlrev_b32_e32 v12, 16, v9
	v_and_b32_e32 v13, 0xffff0000, v9
	v_pk_mul_f32 v[12:13], v[14:15], v[12:13]
	s_nop 0
	v_cvt_pk_bf16_f32 v9, v12, v13
	v_lshlrev_b32_e32 v12, 16, v10
	v_and_b32_e32 v13, 0xffff0000, v10
	s_waitcnt lgkmcnt(0)
	v_pk_mul_f32 v[12:13], v[16:17], v[12:13]
	s_nop 0
	v_cvt_pk_bf16_f32 v10, v12, v13
	v_lshlrev_b32_e32 v12, 16, v11
	v_and_b32_e32 v13, 0xffff0000, v11
	v_pk_mul_f32 v[12:13], v[18:19], v[12:13]
	s_nop 0
	v_cvt_pk_bf16_f32 v11, v12, v13
	global_store_dwordx4 v[2:3], v[8:11], off sc1
	v_add_u32_e32 v2, s38, v145
	v_ashrrev_i32_e32 v3, 31, v2
	ds_read_b128 v[12:15], v7
	ds_read_b128 v[16:19], v7 offset:16
	v_lshlrev_b64 v[2:3], 11, v[2:3]
	v_lshl_add_u64 v[2:3], v[4:5], 0, v[2:3]
	v_mad_i64_i32 v[0:1], s[2:3], v144, s69, v[0:1]
	v_ashrrev_i32_e32 v145, 31, v144
	s_waitcnt vmcnt(6)
	v_mov_b32_e32 v8, v120
	v_mov_b32_e32 v9, v121
	v_mov_b32_e32 v10, v122
	v_mov_b32_e32 v11, v123
	v_lshlrev_b32_e32 v20, 16, v8
	v_and_b32_e32 v21, 0xffff0000, v8
	s_waitcnt lgkmcnt(1)
	v_pk_mul_f32 v[12:13], v[12:13], v[20:21]
	s_nop 0
	v_cvt_pk_bf16_f32 v8, v12, v13
	v_lshlrev_b32_e32 v12, 16, v9
	v_and_b32_e32 v13, 0xffff0000, v9
	v_pk_mul_f32 v[12:13], v[14:15], v[12:13]
	s_nop 0
	v_cvt_pk_bf16_f32 v9, v12, v13
	v_lshlrev_b32_e32 v12, 16, v10
	v_and_b32_e32 v13, 0xffff0000, v10
	s_waitcnt lgkmcnt(0)
	v_pk_mul_f32 v[12:13], v[16:17], v[12:13]
	s_nop 0
	v_cvt_pk_bf16_f32 v10, v12, v13
	v_lshlrev_b32_e32 v12, 16, v11
	v_and_b32_e32 v13, 0xffff0000, v11
	v_pk_mul_f32 v[12:13], v[18:19], v[12:13]
	s_nop 0
	v_cvt_pk_bf16_f32 v11, v12, v13
	global_store_dwordx4 v[2:3], v[8:11], off sc1
	global_load_dwordx4 v[0:3], v[0:1], off
	s_waitcnt vmcnt(0)
	v_lshlrev_b32_e32 v14, 16, v0
	v_lshl_add_u32 v10, v147, 9, v6
	ds_read_b128 v[6:9], v10
	ds_read_b128 v[10:13], v10 offset:16
	v_and_b32_e32 v15, 0xffff0000, v0
	s_waitcnt lgkmcnt(1)
	v_pk_mul_f32 v[6:7], v[6:7], v[14:15]
	s_nop 0
	v_cvt_pk_bf16_f32 v0, v6, v7
	v_lshlrev_b32_e32 v6, 16, v1
	v_and_b32_e32 v7, 0xffff0000, v1
	v_pk_mul_f32 v[6:7], v[8:9], v[6:7]
	s_nop 0
	v_cvt_pk_bf16_f32 v1, v6, v7
	v_lshlrev_b32_e32 v6, 16, v2
	v_and_b32_e32 v7, 0xffff0000, v2
	s_waitcnt lgkmcnt(0)
	v_pk_mul_f32 v[6:7], v[10:11], v[6:7]
	s_nop 0
	v_cvt_pk_bf16_f32 v2, v6, v7
	v_lshlrev_b32_e32 v6, 16, v3
	v_and_b32_e32 v7, 0xffff0000, v3
	v_pk_mul_f32 v[6:7], v[12:13], v[6:7]
	s_nop 0
	v_cvt_pk_bf16_f32 v3, v6, v7
